# P6 SwiGLU epilogue hand-rewritten: ss loads hoisted, packed f32 math on natural accumulator pairs (bit-identical)
# speedup vs baseline: 1.0184x; 1.0074x over previous
.LBB0_674:
	v_lshl_add_u32 v146, s24, 8, v148
	v_lshlrev_b32_e32 v147, 5, v146
	v_add_u32_e32 v254, 0x1000, v147
	global_load_dwordx4 v[156:159], v147, s[10:11]
	global_load_dwordx4 v[160:163], v147, s[10:11] offset:16
	global_load_dwordx4 v[164:167], v147, s[10:11] offset:512
	global_load_dwordx4 v[168:171], v147, s[10:11] offset:528
	global_load_dwordx4 v[172:175], v147, s[10:11] offset:1024
	global_load_dwordx4 v[176:179], v147, s[10:11] offset:1040
	global_load_dwordx4 v[180:183], v147, s[10:11] offset:1536
	global_load_dwordx4 v[184:187], v147, s[10:11] offset:1552
	global_load_dwordx4 v[188:191], v254, s[10:11]
	global_load_dwordx4 v[192:195], v254, s[10:11] offset:16
	global_load_dwordx4 v[196:199], v254, s[10:11] offset:512
	global_load_dwordx4 v[200:203], v254, s[10:11] offset:528
	global_load_dwordx4 v[204:207], v254, s[10:11] offset:1024
	global_load_dwordx4 v[208:211], v254, s[10:11] offset:1040
	global_load_dwordx4 v[212:215], v254, s[10:11] offset:1536
	global_load_dwordx4 v[216:219], v254, s[10:11] offset:1552
	v_mul_u32_u24_e32 v155, 0x2c00, v146
	v_lshl_or_b32 v255, s2, 7, v150
	v_mov_b32_e32 v252, 0xbfb8aa3b
	v_mov_b32_e32 v253, 1.0
	v_lshl_add_u32 v155, v255, 1, v155
	s_andn2_b64 vcc, exec, s[0:1]
	s_mov_b64 s[0:1], -1
	s_waitcnt vmcnt(14)
	v_add_f32_e32 v156, v156, v157
	v_add_f32_e32 v158, v158, v159
	v_add_f32_e32 v160, v160, v161
	v_add_f32_e32 v162, v162, v163
	v_add_f32_e32 v156, v156, v158
	v_add_f32_e32 v160, v160, v162
	v_add_f32_e32 v156, v156, v160
	v_fmamk_f32 v156, v156, 0x3a000000, v154
	v_rsq_f32_e32 v146, v156
	v_mov_b32_e32 v147, v155
	v_pk_mul_f32 v[116:117], v[116:117], v[146:147] op_sel_hi:[1,0]
	v_pk_mul_f32 v[118:119], v[118:119], v[146:147] op_sel_hi:[1,0]
	v_pk_mul_f32 v[112:113], v[112:113], v[146:147] op_sel_hi:[1,0]
	v_pk_mul_f32 v[114:115], v[114:115], v[146:147] op_sel_hi:[1,0]
	v_pk_mul_f32 v[124:125], v[124:125], v[146:147] op_sel_hi:[1,0]
	v_pk_mul_f32 v[126:127], v[126:127], v[146:147] op_sel_hi:[1,0]
	v_pk_mul_f32 v[120:121], v[120:121], v[146:147] op_sel_hi:[1,0]
	v_pk_mul_f32 v[122:123], v[122:123], v[146:147] op_sel_hi:[1,0]
	v_pk_mul_f32 v[156:157], v[116:117], v[252:253] op_sel_hi:[1,0]
	v_pk_mul_f32 v[158:159], v[118:119], v[252:253] op_sel_hi:[1,0]
	v_pk_mul_f32 v[160:161], v[112:113], v[252:253] op_sel_hi:[1,0]
	v_pk_mul_f32 v[162:163], v[114:115], v[252:253] op_sel_hi:[1,0]
	v_exp_f32_e32 v156, v156
	v_exp_f32_e32 v157, v157
	v_exp_f32_e32 v158, v158
	v_exp_f32_e32 v159, v159
	v_exp_f32_e32 v160, v160
	v_exp_f32_e32 v161, v161
	v_exp_f32_e32 v162, v162
	v_exp_f32_e32 v163, v163
	v_pk_add_f32 v[156:157], v[156:157], v[252:253] op_sel:[0,1]
	v_pk_add_f32 v[158:159], v[158:159], v[252:253] op_sel:[0,1]
	v_pk_add_f32 v[160:161], v[160:161], v[252:253] op_sel:[0,1]
	v_pk_add_f32 v[162:163], v[162:163], v[252:253] op_sel:[0,1]
	v_rcp_f32_e32 v156, v156
	v_rcp_f32_e32 v157, v157
	v_rcp_f32_e32 v158, v158
	v_rcp_f32_e32 v159, v159
	v_rcp_f32_e32 v160, v160
	v_rcp_f32_e32 v161, v161
	v_rcp_f32_e32 v162, v162
	v_rcp_f32_e32 v163, v163
	v_pk_mul_f32 v[116:117], v[116:117], v[156:157]
	v_pk_mul_f32 v[118:119], v[118:119], v[158:159]
	v_pk_mul_f32 v[112:113], v[112:113], v[160:161]
	v_pk_mul_f32 v[114:115], v[114:115], v[162:163]
	v_pk_mul_f32 v[116:117], v[124:125], v[116:117]
	v_pk_mul_f32 v[118:119], v[126:127], v[118:119]
	v_pk_mul_f32 v[112:113], v[120:121], v[112:113]
	v_pk_mul_f32 v[114:115], v[122:123], v[114:115]
	v_cvt_pk_bf16_f32 v120, v116, v117
	v_cvt_pk_bf16_f32 v121, v118, v119
	v_cvt_pk_bf16_f32 v122, v112, v113
	v_cvt_pk_bf16_f32 v123, v114, v115
	global_store_dwordx4 v147, v[120:123], s[8:9]
	s_waitcnt vmcnt(13)
	v_add_f32_e32 v164, v164, v165
	v_add_f32_e32 v166, v166, v167
	v_add_f32_e32 v168, v168, v169
	v_add_f32_e32 v170, v170, v171
	v_add_f32_e32 v164, v164, v166
	v_add_f32_e32 v168, v168, v170
	v_add_f32_e32 v164, v164, v168
	v_fmamk_f32 v164, v164, 0x3a000000, v154
	v_rsq_f32_e32 v146, v164
	v_add_u32_e32 v147, 0x2c000, v155
	v_pk_mul_f32 v[100:101], v[100:101], v[146:147] op_sel_hi:[1,0]
	v_pk_mul_f32 v[102:103], v[102:103], v[146:147] op_sel_hi:[1,0]
	v_pk_mul_f32 v[96:97], v[96:97], v[146:147] op_sel_hi:[1,0]
	v_pk_mul_f32 v[98:99], v[98:99], v[146:147] op_sel_hi:[1,0]
	v_pk_mul_f32 v[108:109], v[108:109], v[146:147] op_sel_hi:[1,0]
	v_pk_mul_f32 v[110:111], v[110:111], v[146:147] op_sel_hi:[1,0]
	v_pk_mul_f32 v[104:105], v[104:105], v[146:147] op_sel_hi:[1,0]
	v_pk_mul_f32 v[106:107], v[106:107], v[146:147] op_sel_hi:[1,0]
	v_pk_mul_f32 v[164:165], v[100:101], v[252:253] op_sel_hi:[1,0]
	v_pk_mul_f32 v[166:167], v[102:103], v[252:253] op_sel_hi:[1,0]
	v_pk_mul_f32 v[168:169], v[96:97], v[252:253] op_sel_hi:[1,0]
	v_pk_mul_f32 v[170:171], v[98:99], v[252:253] op_sel_hi:[1,0]
	v_exp_f32_e32 v164, v164
	v_exp_f32_e32 v165, v165
	v_exp_f32_e32 v166, v166
	v_exp_f32_e32 v167, v167
	v_exp_f32_e32 v168, v168
	v_exp_f32_e32 v169, v169
	v_exp_f32_e32 v170, v170
	v_exp_f32_e32 v171, v171
	v_pk_add_f32 v[164:165], v[164:165], v[252:253] op_sel:[0,1]
	v_pk_add_f32 v[166:167], v[166:167], v[252:253] op_sel:[0,1]
	v_pk_add_f32 v[168:169], v[168:169], v[252:253] op_sel:[0,1]
	v_pk_add_f32 v[170:171], v[170:171], v[252:253] op_sel:[0,1]
	v_rcp_f32_e32 v164, v164
	v_rcp_f32_e32 v165, v165
	v_rcp_f32_e32 v166, v166
	v_rcp_f32_e32 v167, v167
	v_rcp_f32_e32 v168, v168
	v_rcp_f32_e32 v169, v169
	v_rcp_f32_e32 v170, v170
	v_rcp_f32_e32 v171, v171
	v_pk_mul_f32 v[100:101], v[100:101], v[164:165]
	v_pk_mul_f32 v[102:103], v[102:103], v[166:167]
	v_pk_mul_f32 v[96:97], v[96:97], v[168:169]
	v_pk_mul_f32 v[98:99], v[98:99], v[170:171]
	v_pk_mul_f32 v[100:101], v[108:109], v[100:101]
	v_pk_mul_f32 v[102:103], v[110:111], v[102:103]
	v_pk_mul_f32 v[96:97], v[104:105], v[96:97]
	v_pk_mul_f32 v[98:99], v[106:107], v[98:99]
	v_cvt_pk_bf16_f32 v104, v100, v101
	v_cvt_pk_bf16_f32 v105, v102, v103
	v_cvt_pk_bf16_f32 v106, v96, v97
	v_cvt_pk_bf16_f32 v107, v98, v99
	global_store_dwordx4 v147, v[104:107], s[8:9]
	s_waitcnt vmcnt(12)
	v_add_f32_e32 v172, v172, v173
	v_add_f32_e32 v174, v174, v175
	v_add_f32_e32 v176, v176, v177
	v_add_f32_e32 v178, v178, v179
	v_add_f32_e32 v172, v172, v174
	v_add_f32_e32 v176, v176, v178
	v_add_f32_e32 v172, v172, v176
	v_fmamk_f32 v172, v172, 0x3a000000, v154
	v_rsq_f32_e32 v146, v172
	v_add_u32_e32 v147, 0x58000, v155
	v_pk_mul_f32 v[84:85], v[84:85], v[146:147] op_sel_hi:[1,0]
	v_pk_mul_f32 v[86:87], v[86:87], v[146:147] op_sel_hi:[1,0]
	v_pk_mul_f32 v[80:81], v[80:81], v[146:147] op_sel_hi:[1,0]
	v_pk_mul_f32 v[82:83], v[82:83], v[146:147] op_sel_hi:[1,0]
	v_pk_mul_f32 v[92:93], v[92:93], v[146:147] op_sel_hi:[1,0]
	v_pk_mul_f32 v[94:95], v[94:95], v[146:147] op_sel_hi:[1,0]
	v_pk_mul_f32 v[88:89], v[88:89], v[146:147] op_sel_hi:[1,0]
	v_pk_mul_f32 v[90:91], v[90:91], v[146:147] op_sel_hi:[1,0]
	v_pk_mul_f32 v[172:173], v[84:85], v[252:253] op_sel_hi:[1,0]
	v_pk_mul_f32 v[174:175], v[86:87], v[252:253] op_sel_hi:[1,0]
	v_pk_mul_f32 v[176:177], v[80:81], v[252:253] op_sel_hi:[1,0]
	v_pk_mul_f32 v[178:179], v[82:83], v[252:253] op_sel_hi:[1,0]
	v_exp_f32_e32 v172, v172
	v_exp_f32_e32 v173, v173
	v_exp_f32_e32 v174, v174
	v_exp_f32_e32 v175, v175
	v_exp_f32_e32 v176, v176
	v_exp_f32_e32 v177, v177
	v_exp_f32_e32 v178, v178
	v_exp_f32_e32 v179, v179
	v_pk_add_f32 v[172:173], v[172:173], v[252:253] op_sel:[0,1]
	v_pk_add_f32 v[174:175], v[174:175], v[252:253] op_sel:[0,1]
	v_pk_add_f32 v[176:177], v[176:177], v[252:253] op_sel:[0,1]
	v_pk_add_f32 v[178:179], v[178:179], v[252:253] op_sel:[0,1]
	v_rcp_f32_e32 v172, v172
	v_rcp_f32_e32 v173, v173
	v_rcp_f32_e32 v174, v174
	v_rcp_f32_e32 v175, v175
	v_rcp_f32_e32 v176, v176
	v_rcp_f32_e32 v177, v177
	v_rcp_f32_e32 v178, v178
	v_rcp_f32_e32 v179, v179
	v_pk_mul_f32 v[84:85], v[84:85], v[172:173]
	v_pk_mul_f32 v[86:87], v[86:87], v[174:175]
	v_pk_mul_f32 v[80:81], v[80:81], v[176:177]
	v_pk_mul_f32 v[82:83], v[82:83], v[178:179]
	v_pk_mul_f32 v[84:85], v[92:93], v[84:85]
	v_pk_mul_f32 v[86:87], v[94:95], v[86:87]
	v_pk_mul_f32 v[80:81], v[88:89], v[80:81]
	v_pk_mul_f32 v[82:83], v[90:91], v[82:83]
	v_cvt_pk_bf16_f32 v88, v84, v85
	v_cvt_pk_bf16_f32 v89, v86, v87
	v_cvt_pk_bf16_f32 v90, v80, v81
	v_cvt_pk_bf16_f32 v91, v82, v83
	global_store_dwordx4 v147, v[88:91], s[8:9]
	s_waitcnt vmcnt(11)
	v_add_f32_e32 v180, v180, v181
	v_add_f32_e32 v182, v182, v183
	v_add_f32_e32 v184, v184, v185
	v_add_f32_e32 v186, v186, v187
	v_add_f32_e32 v180, v180, v182
	v_add_f32_e32 v184, v184, v186
	v_add_f32_e32 v180, v180, v184
	v_fmamk_f32 v180, v180, 0x3a000000, v154
	v_rsq_f32_e32 v146, v180
	v_add_u32_e32 v147, 0x84000, v155
	v_pk_mul_f32 v[68:69], v[68:69], v[146:147] op_sel_hi:[1,0]
	v_pk_mul_f32 v[70:71], v[70:71], v[146:147] op_sel_hi:[1,0]
	v_pk_mul_f32 v[64:65], v[64:65], v[146:147] op_sel_hi:[1,0]
	v_pk_mul_f32 v[66:67], v[66:67], v[146:147] op_sel_hi:[1,0]
	v_pk_mul_f32 v[76:77], v[76:77], v[146:147] op_sel_hi:[1,0]
	v_pk_mul_f32 v[78:79], v[78:79], v[146:147] op_sel_hi:[1,0]
	v_pk_mul_f32 v[72:73], v[72:73], v[146:147] op_sel_hi:[1,0]
	v_pk_mul_f32 v[74:75], v[74:75], v[146:147] op_sel_hi:[1,0]
	v_pk_mul_f32 v[180:181], v[68:69], v[252:253] op_sel_hi:[1,0]
	v_pk_mul_f32 v[182:183], v[70:71], v[252:253] op_sel_hi:[1,0]
	v_pk_mul_f32 v[184:185], v[64:65], v[252:253] op_sel_hi:[1,0]
	v_pk_mul_f32 v[186:187], v[66:67], v[252:253] op_sel_hi:[1,0]
	v_exp_f32_e32 v180, v180
	v_exp_f32_e32 v181, v181
	v_exp_f32_e32 v182, v182
	v_exp_f32_e32 v183, v183
	v_exp_f32_e32 v184, v184
	v_exp_f32_e32 v185, v185
	v_exp_f32_e32 v186, v186
	v_exp_f32_e32 v187, v187
	v_pk_add_f32 v[180:181], v[180:181], v[252:253] op_sel:[0,1]
	v_pk_add_f32 v[182:183], v[182:183], v[252:253] op_sel:[0,1]
	v_pk_add_f32 v[184:185], v[184:185], v[252:253] op_sel:[0,1]
	v_pk_add_f32 v[186:187], v[186:187], v[252:253] op_sel:[0,1]
	v_rcp_f32_e32 v180, v180
	v_rcp_f32_e32 v181, v181
	v_rcp_f32_e32 v182, v182
	v_rcp_f32_e32 v183, v183
	v_rcp_f32_e32 v184, v184
	v_rcp_f32_e32 v185, v185
	v_rcp_f32_e32 v186, v186
	v_rcp_f32_e32 v187, v187
	v_pk_mul_f32 v[68:69], v[68:69], v[180:181]
	v_pk_mul_f32 v[70:71], v[70:71], v[182:183]
	v_pk_mul_f32 v[64:65], v[64:65], v[184:185]
	v_pk_mul_f32 v[66:67], v[66:67], v[186:187]
	v_pk_mul_f32 v[68:69], v[76:77], v[68:69]
	v_pk_mul_f32 v[70:71], v[78:79], v[70:71]
	v_pk_mul_f32 v[64:65], v[72:73], v[64:65]
	v_pk_mul_f32 v[66:67], v[74:75], v[66:67]
	v_cvt_pk_bf16_f32 v72, v68, v69
	v_cvt_pk_bf16_f32 v73, v70, v71
	v_cvt_pk_bf16_f32 v74, v64, v65
	v_cvt_pk_bf16_f32 v75, v66, v67
	global_store_dwordx4 v147, v[72:75], s[8:9]
	s_waitcnt vmcnt(10)
	v_add_f32_e32 v188, v188, v189
	v_add_f32_e32 v190, v190, v191
	v_add_f32_e32 v192, v192, v193
	v_add_f32_e32 v194, v194, v195
	v_add_f32_e32 v188, v188, v190
	v_add_f32_e32 v192, v192, v194
	v_add_f32_e32 v188, v188, v192
	v_fmamk_f32 v188, v188, 0x3a000000, v154
	v_rsq_f32_e32 v146, v188
	v_add_u32_e32 v147, 0x160000, v155
	v_pk_mul_f32 v[52:53], v[52:53], v[146:147] op_sel_hi:[1,0]
	v_pk_mul_f32 v[54:55], v[54:55], v[146:147] op_sel_hi:[1,0]
	v_pk_mul_f32 v[48:49], v[48:49], v[146:147] op_sel_hi:[1,0]
	v_pk_mul_f32 v[50:51], v[50:51], v[146:147] op_sel_hi:[1,0]
	v_pk_mul_f32 v[60:61], v[60:61], v[146:147] op_sel_hi:[1,0]
	v_pk_mul_f32 v[62:63], v[62:63], v[146:147] op_sel_hi:[1,0]
	v_pk_mul_f32 v[56:57], v[56:57], v[146:147] op_sel_hi:[1,0]
	v_pk_mul_f32 v[58:59], v[58:59], v[146:147] op_sel_hi:[1,0]
	v_pk_mul_f32 v[188:189], v[52:53], v[252:253] op_sel_hi:[1,0]
	v_pk_mul_f32 v[190:191], v[54:55], v[252:253] op_sel_hi:[1,0]
	v_pk_mul_f32 v[192:193], v[48:49], v[252:253] op_sel_hi:[1,0]
	v_pk_mul_f32 v[194:195], v[50:51], v[252:253] op_sel_hi:[1,0]
	v_exp_f32_e32 v188, v188
	v_exp_f32_e32 v189, v189
	v_exp_f32_e32 v190, v190
	v_exp_f32_e32 v191, v191
	v_exp_f32_e32 v192, v192
	v_exp_f32_e32 v193, v193
	v_exp_f32_e32 v194, v194
	v_exp_f32_e32 v195, v195
	v_pk_add_f32 v[188:189], v[188:189], v[252:253] op_sel:[0,1]
	v_pk_add_f32 v[190:191], v[190:191], v[252:253] op_sel:[0,1]
	v_pk_add_f32 v[192:193], v[192:193], v[252:253] op_sel:[0,1]
	v_pk_add_f32 v[194:195], v[194:195], v[252:253] op_sel:[0,1]
	v_rcp_f32_e32 v188, v188
	v_rcp_f32_e32 v189, v189
	v_rcp_f32_e32 v190, v190
	v_rcp_f32_e32 v191, v191
	v_rcp_f32_e32 v192, v192
	v_rcp_f32_e32 v193, v193
	v_rcp_f32_e32 v194, v194
	v_rcp_f32_e32 v195, v195
	v_pk_mul_f32 v[52:53], v[52:53], v[188:189]
	v_pk_mul_f32 v[54:55], v[54:55], v[190:191]
	v_pk_mul_f32 v[48:49], v[48:49], v[192:193]
	v_pk_mul_f32 v[50:51], v[50:51], v[194:195]
	v_pk_mul_f32 v[52:53], v[60:61], v[52:53]
	v_pk_mul_f32 v[54:55], v[62:63], v[54:55]
	v_pk_mul_f32 v[48:49], v[56:57], v[48:49]
	v_pk_mul_f32 v[50:51], v[58:59], v[50:51]
	v_cvt_pk_bf16_f32 v56, v52, v53
	v_cvt_pk_bf16_f32 v57, v54, v55
	v_cvt_pk_bf16_f32 v58, v48, v49
	v_cvt_pk_bf16_f32 v59, v50, v51
	global_store_dwordx4 v147, v[56:59], s[8:9]
	s_waitcnt vmcnt(9)
	v_add_f32_e32 v196, v196, v197
	v_add_f32_e32 v198, v198, v199
	v_add_f32_e32 v200, v200, v201
	v_add_f32_e32 v202, v202, v203
	v_add_f32_e32 v196, v196, v198
	v_add_f32_e32 v200, v200, v202
	v_add_f32_e32 v196, v196, v200
	v_fmamk_f32 v196, v196, 0x3a000000, v154
	v_rsq_f32_e32 v146, v196
	v_add_u32_e32 v147, 0x18c000, v155
	v_pk_mul_f32 v[36:37], v[36:37], v[146:147] op_sel_hi:[1,0]
	v_pk_mul_f32 v[38:39], v[38:39], v[146:147] op_sel_hi:[1,0]
	v_pk_mul_f32 v[32:33], v[32:33], v[146:147] op_sel_hi:[1,0]
	v_pk_mul_f32 v[34:35], v[34:35], v[146:147] op_sel_hi:[1,0]
	v_pk_mul_f32 v[44:45], v[44:45], v[146:147] op_sel_hi:[1,0]
	v_pk_mul_f32 v[46:47], v[46:47], v[146:147] op_sel_hi:[1,0]
	v_pk_mul_f32 v[40:41], v[40:41], v[146:147] op_sel_hi:[1,0]
	v_pk_mul_f32 v[42:43], v[42:43], v[146:147] op_sel_hi:[1,0]
	v_pk_mul_f32 v[196:197], v[36:37], v[252:253] op_sel_hi:[1,0]
	v_pk_mul_f32 v[198:199], v[38:39], v[252:253] op_sel_hi:[1,0]
	v_pk_mul_f32 v[200:201], v[32:33], v[252:253] op_sel_hi:[1,0]
	v_pk_mul_f32 v[202:203], v[34:35], v[252:253] op_sel_hi:[1,0]
	v_exp_f32_e32 v196, v196
	v_exp_f32_e32 v197, v197
	v_exp_f32_e32 v198, v198
	v_exp_f32_e32 v199, v199
	v_exp_f32_e32 v200, v200
	v_exp_f32_e32 v201, v201
	v_exp_f32_e32 v202, v202
	v_exp_f32_e32 v203, v203
	v_pk_add_f32 v[196:197], v[196:197], v[252:253] op_sel:[0,1]
	v_pk_add_f32 v[198:199], v[198:199], v[252:253] op_sel:[0,1]
	v_pk_add_f32 v[200:201], v[200:201], v[252:253] op_sel:[0,1]
	v_pk_add_f32 v[202:203], v[202:203], v[252:253] op_sel:[0,1]
	v_rcp_f32_e32 v196, v196
	v_rcp_f32_e32 v197, v197
	v_rcp_f32_e32 v198, v198
	v_rcp_f32_e32 v199, v199
	v_rcp_f32_e32 v200, v200
	v_rcp_f32_e32 v201, v201
	v_rcp_f32_e32 v202, v202
	v_rcp_f32_e32 v203, v203
	v_pk_mul_f32 v[36:37], v[36:37], v[196:197]
	v_pk_mul_f32 v[38:39], v[38:39], v[198:199]
	v_pk_mul_f32 v[32:33], v[32:33], v[200:201]
	v_pk_mul_f32 v[34:35], v[34:35], v[202:203]
	v_pk_mul_f32 v[36:37], v[44:45], v[36:37]
	v_pk_mul_f32 v[38:39], v[46:47], v[38:39]
	v_pk_mul_f32 v[32:33], v[40:41], v[32:33]
	v_pk_mul_f32 v[34:35], v[42:43], v[34:35]
	v_cvt_pk_bf16_f32 v40, v36, v37
	v_cvt_pk_bf16_f32 v41, v38, v39
	v_cvt_pk_bf16_f32 v42, v32, v33
	v_cvt_pk_bf16_f32 v43, v34, v35
	global_store_dwordx4 v147, v[40:43], s[8:9]
	s_waitcnt vmcnt(8)
	v_add_f32_e32 v204, v204, v205
	v_add_f32_e32 v206, v206, v207
	v_add_f32_e32 v208, v208, v209
	v_add_f32_e32 v210, v210, v211
	v_add_f32_e32 v204, v204, v206
	v_add_f32_e32 v208, v208, v210
	v_add_f32_e32 v204, v204, v208
	v_fmamk_f32 v204, v204, 0x3a000000, v154
	v_rsq_f32_e32 v146, v204
	v_add_u32_e32 v147, 0x1b8000, v155
	v_pk_mul_f32 v[20:21], v[20:21], v[146:147] op_sel_hi:[1,0]
	v_pk_mul_f32 v[22:23], v[22:23], v[146:147] op_sel_hi:[1,0]
	v_pk_mul_f32 v[16:17], v[16:17], v[146:147] op_sel_hi:[1,0]
	v_pk_mul_f32 v[18:19], v[18:19], v[146:147] op_sel_hi:[1,0]
	v_pk_mul_f32 v[28:29], v[28:29], v[146:147] op_sel_hi:[1,0]
	v_pk_mul_f32 v[30:31], v[30:31], v[146:147] op_sel_hi:[1,0]
	v_pk_mul_f32 v[24:25], v[24:25], v[146:147] op_sel_hi:[1,0]
	v_pk_mul_f32 v[26:27], v[26:27], v[146:147] op_sel_hi:[1,0]
	v_pk_mul_f32 v[204:205], v[20:21], v[252:253] op_sel_hi:[1,0]
	v_pk_mul_f32 v[206:207], v[22:23], v[252:253] op_sel_hi:[1,0]
	v_pk_mul_f32 v[208:209], v[16:17], v[252:253] op_sel_hi:[1,0]
	v_pk_mul_f32 v[210:211], v[18:19], v[252:253] op_sel_hi:[1,0]
	v_exp_f32_e32 v204, v204
	v_exp_f32_e32 v205, v205
	v_exp_f32_e32 v206, v206
	v_exp_f32_e32 v207, v207
	v_exp_f32_e32 v208, v208
	v_exp_f32_e32 v209, v209
	v_exp_f32_e32 v210, v210
	v_exp_f32_e32 v211, v211
	v_pk_add_f32 v[204:205], v[204:205], v[252:253] op_sel:[0,1]
	v_pk_add_f32 v[206:207], v[206:207], v[252:253] op_sel:[0,1]
	v_pk_add_f32 v[208:209], v[208:209], v[252:253] op_sel:[0,1]
	v_pk_add_f32 v[210:211], v[210:211], v[252:253] op_sel:[0,1]
	v_rcp_f32_e32 v204, v204
	v_rcp_f32_e32 v205, v205
	v_rcp_f32_e32 v206, v206
	v_rcp_f32_e32 v207, v207
	v_rcp_f32_e32 v208, v208
	v_rcp_f32_e32 v209, v209
	v_rcp_f32_e32 v210, v210
	v_rcp_f32_e32 v211, v211
	v_pk_mul_f32 v[20:21], v[20:21], v[204:205]
	v_pk_mul_f32 v[22:23], v[22:23], v[206:207]
	v_pk_mul_f32 v[16:17], v[16:17], v[208:209]
	v_pk_mul_f32 v[18:19], v[18:19], v[210:211]
	v_pk_mul_f32 v[20:21], v[28:29], v[20:21]
	v_pk_mul_f32 v[22:23], v[30:31], v[22:23]
	v_pk_mul_f32 v[16:17], v[24:25], v[16:17]
	v_pk_mul_f32 v[18:19], v[26:27], v[18:19]
	v_cvt_pk_bf16_f32 v24, v20, v21
	v_cvt_pk_bf16_f32 v25, v22, v23
	v_cvt_pk_bf16_f32 v26, v16, v17
	v_cvt_pk_bf16_f32 v27, v18, v19
	global_store_dwordx4 v147, v[24:27], s[8:9]
	s_waitcnt vmcnt(7)
	v_add_f32_e32 v212, v212, v213
	v_add_f32_e32 v214, v214, v215
	v_add_f32_e32 v216, v216, v217
	v_add_f32_e32 v218, v218, v219
	v_add_f32_e32 v212, v212, v214
	v_add_f32_e32 v216, v216, v218
	v_add_f32_e32 v212, v212, v216
	v_fmamk_f32 v212, v212, 0x3a000000, v154
	v_rsq_f32_e32 v146, v212
	v_add_u32_e32 v147, 0x1e4000, v155
	v_pk_mul_f32 v[8:9], v[8:9], v[146:147] op_sel_hi:[1,0]
	v_pk_mul_f32 v[10:11], v[10:11], v[146:147] op_sel_hi:[1,0]
	v_pk_mul_f32 v[0:1], v[0:1], v[146:147] op_sel_hi:[1,0]
	v_pk_mul_f32 v[2:3], v[2:3], v[146:147] op_sel_hi:[1,0]
	v_pk_mul_f32 v[12:13], v[12:13], v[146:147] op_sel_hi:[1,0]
	v_pk_mul_f32 v[14:15], v[14:15], v[146:147] op_sel_hi:[1,0]
	v_pk_mul_f32 v[4:5], v[4:5], v[146:147] op_sel_hi:[1,0]
	v_pk_mul_f32 v[6:7], v[6:7], v[146:147] op_sel_hi:[1,0]
	v_pk_mul_f32 v[212:213], v[8:9], v[252:253] op_sel_hi:[1,0]
	v_pk_mul_f32 v[214:215], v[10:11], v[252:253] op_sel_hi:[1,0]
	v_pk_mul_f32 v[216:217], v[0:1], v[252:253] op_sel_hi:[1,0]
	v_pk_mul_f32 v[218:219], v[2:3], v[252:253] op_sel_hi:[1,0]
	v_exp_f32_e32 v212, v212
	v_exp_f32_e32 v213, v213
	v_exp_f32_e32 v214, v214
	v_exp_f32_e32 v215, v215
	v_exp_f32_e32 v216, v216
	v_exp_f32_e32 v217, v217
	v_exp_f32_e32 v218, v218
	v_exp_f32_e32 v219, v219
	v_pk_add_f32 v[212:213], v[212:213], v[252:253] op_sel:[0,1]
	v_pk_add_f32 v[214:215], v[214:215], v[252:253] op_sel:[0,1]
	v_pk_add_f32 v[216:217], v[216:217], v[252:253] op_sel:[0,1]
	v_pk_add_f32 v[218:219], v[218:219], v[252:253] op_sel:[0,1]
	v_rcp_f32_e32 v212, v212
	v_rcp_f32_e32 v213, v213
	v_rcp_f32_e32 v214, v214
	v_rcp_f32_e32 v215, v215
	v_rcp_f32_e32 v216, v216
	v_rcp_f32_e32 v217, v217
	v_rcp_f32_e32 v218, v218
	v_rcp_f32_e32 v219, v219
	v_pk_mul_f32 v[8:9], v[8:9], v[212:213]
	v_pk_mul_f32 v[10:11], v[10:11], v[214:215]
	v_pk_mul_f32 v[0:1], v[0:1], v[216:217]
	v_pk_mul_f32 v[2:3], v[2:3], v[218:219]
	v_pk_mul_f32 v[8:9], v[12:13], v[8:9]
	v_pk_mul_f32 v[10:11], v[14:15], v[10:11]
	v_pk_mul_f32 v[0:1], v[4:5], v[0:1]
	v_pk_mul_f32 v[2:3], v[6:7], v[2:3]
	v_cvt_pk_bf16_f32 v4, v8, v9
	v_cvt_pk_bf16_f32 v5, v10, v11
	v_cvt_pk_bf16_f32 v6, v0, v1
	v_cvt_pk_bf16_f32 v7, v2, v3
	global_store_dwordx4 v147, v[4:7], s[8:9]
	s_cbranch_vccnz .LBB0_667
	s_andn2_b64 vcc, exec, s[6:7]
	s_cbranch_vccnz .LBB0_666
	s_barrier
	s_branch .LBB0_666

	.amdhsa_kernel _Z9hymba_fwd4Args
		.amdhsa_group_segment_fixed_size 0
		.amdhsa_private_segment_fixed_size 0
		.amdhsa_kernarg_size 416
		.amdhsa_user_sgpr_count 2
		.amdhsa_user_sgpr_dispatch_ptr 0
		.amdhsa_user_sgpr_queue_ptr 0
		.amdhsa_user_sgpr_kernarg_segment_ptr 1
		.amdhsa_user_sgpr_dispatch_id 0
		.amdhsa_user_sgpr_kernarg_preload_length 0
		.amdhsa_user_sgpr_kernarg_preload_offset 0
		.amdhsa_user_sgpr_private_segment_size 0
		.amdhsa_uses_dynamic_stack 0
		.amdhsa_enable_private_segment 0
		.amdhsa_system_sgpr_workgroup_id_x 1
		.amdhsa_system_sgpr_workgroup_id_y 0
		.amdhsa_system_sgpr_workgroup_id_z 0
		.amdhsa_system_sgpr_workgroup_info 0
		.amdhsa_system_vgpr_workitem_id 2
		.amdhsa_next_free_vgpr 256
		.amdhsa_next_free_sgpr 102
		.amdhsa_accum_offset 256
		.amdhsa_reserve_vcc 1
		.amdhsa_float_round_mode_32 0
		.amdhsa_float_round_mode_16_64 0
		.amdhsa_float_denorm_mode_32 3
		.amdhsa_float_denorm_mode_16_64 3
		.amdhsa_dx10_clamp 1
		.amdhsa_ieee_mode 1
		.amdhsa_fp16_overflow 0
		.amdhsa_tg_split 0
		.amdhsa_exception_fp_ieee_invalid_op 0
		.amdhsa_exception_fp_denorm_src 0
		.amdhsa_exception_fp_ieee_div_zero 0
		.amdhsa_exception_fp_ieee_overflow 0
		.amdhsa_exception_fp_ieee_underflow 0
		.amdhsa_exception_fp_ieee_inexact 0
		.amdhsa_exception_int_div_zero 0
	.end_amdhsa_kernel

amdhsa.kernels:
  - .agpr_count:     0
    .args:
      - .offset:         0
        .size:           160
        .value_kind:     by_value
      - .offset:         160
        .size:           4
        .value_kind:     hidden_block_count_x
      - .offset:         164
        .size:           4
        .value_kind:     hidden_block_count_y
      - .offset:         168
        .size:           4
        .value_kind:     hidden_block_count_z
      - .offset:         172
        .size:           2
        .value_kind:     hidden_group_size_x
      - .offset:         174
        .size:           2
        .value_kind:     hidden_group_size_y
      - .offset:         176
        .size:           2
        .value_kind:     hidden_group_size_z
      - .offset:         178
        .size:           2
        .value_kind:     hidden_remainder_x
      - .offset:         180
        .size:           2
        .value_kind:     hidden_remainder_y
      - .offset:         182
        .size:           2
        .value_kind:     hidden_remainder_z
      - .offset:         200
        .size:           8
        .value_kind:     hidden_global_offset_x
      - .offset:         208
        .size:           8
        .value_kind:     hidden_global_offset_y
      - .offset:         216
        .size:           8
        .value_kind:     hidden_global_offset_z
      - .offset:         224
        .size:           2
        .value_kind:     hidden_grid_dims
      - .offset:         248
        .size:           8
        .value_kind:     hidden_multigrid_sync_arg
      - .offset:         280
        .size:           4
        .value_kind:     hidden_dynamic_lds_size
    .group_segment_fixed_size: 0
    .kernarg_segment_align: 8
    .kernarg_segment_size: 416
    .language:       OpenCL C
    .language_version:
      - 2
      - 0
    .max_flat_workgroup_size: 512
    .name:           _Z9hymba_fwd4Args
    .private_segment_fixed_size: 0
    .sgpr_count:     108
    .sgpr_spill_count: 83
    .symbol:         _Z9hymba_fwd4Args.kd
    .uniform_work_group_size: 1
    .uses_dynamic_stack: false
    .vgpr_count:     256
    .vgpr_spill_count: 0
    .wavefront_size: 64
